# E68: E66 plus diff QK k-step-2 fragment pair read in consumption order with a split lgkmcnt(1)/(0) wait
# baseline (speedup 1.0000x reference)
; template <int NQK>
; __device__ __forceinline__ void qkt_mi(f32x16& p0, f32x16& p1, const char* Ks, const bf16x8* qr, int r32, int hi, const f32x16& minit) {
;   constexpr int KROW = NQK * 32 + 16;
; #pragma unroll
;   for (int d0 = 0; d0 < NQK; ++d0) { const int cb = (d0 * 16 + hi * 8) * 2;
;     bf16x8 b0 = *reinterpret_cast<const bf16x8*>(Ks + r32 * KROW + cb);
;     bf16x8 b1 = *reinterpret_cast<const bf16x8*>(Ks + (32 + r32) * KROW + cb);
;     if (d0 == 0) { p0 = __builtin_amdgcn_mfma_f32_32x32x16_bf16(b0, qr[0], minit, 0, 0, 0); p1 = __builtin_amdgcn_mfma_f32_32x32x16_bf16(b1, qr[0], minit, 0, 0, 0); }
;     else { p0 = __builtin_amdgcn_mfma_f32_32x32x16_bf16(b0, qr[d0], p0, 0, 0, 0); p1 = __builtin_amdgcn_mfma_f32_32x32x16_bf16(b1, qr[d0], p1, 0, 0, 0); } }
; }
; __device__ __forceinline__ void decide_mi(f32x16& p0, f32x16& p1, f32x16& minit, float& M, float& alpha, const float thr2, const bool first) {
;   float pmax = p0[0];
; #pragma unroll
;   for (int r = 1; r < 16; ++r) pmax = fmaxf(pmax, p0[r]);
; #pragma unroll
;   for (int r = 0; r < 16; ++r) pmax = fmaxf(pmax, p1[r]);
;   { auto rr = __builtin_amdgcn_permlane32_swap(__float_as_uint(pmax), __float_as_uint(pmax), false, false);
;     pmax = fmaxf(__uint_as_float(rr[0]), __uint_as_float(rr[1])); }
;   if (__builtin_expect(!first && __all(pmax <= thr2), 1)) { alpha = 1.f; }
;   else { const float delta = first ? pmax : fmaxf(pmax, 0.f); alpha = first ? 1.f : __builtin_amdgcn_exp2f(-delta); M += delta;
; #pragma unroll
;     for (int r = 0; r < 16; ++r) { p0[r] -= delta; p1[r] -= delta; minit[r] = -M; } }
; }
.LBB0_1286:
	s_mov_b32 s15, s58
	s_mov_b32 s58, s8
	s_mul_i32 s8, s15, 0x2400
	v_add_u32_e32 v215, s8, v221
	ds_read_b128 v[232:235], v215 offset:53760
	ds_read_b128 v[112:115], v215 offset:49152
	ds_read_b128 v[236:239], v215 offset:49184
	v_exp_f32_e32 v96, v96
	v_exp_f32_e32 v97, v97
	v_exp_f32_e32 v99, v99
	s_waitcnt lgkmcnt(1)
	v_mfma_f32_32x32x16_bf16 v[128:143], v[112:115], v[146:149], v[80:95]
	s_waitcnt lgkmcnt(0)
	v_mfma_f32_32x32x16_bf16 v[128:143], v[236:239], v[150:153], v[128:143]
	v_exp_f32_e32 v100, v100
	v_exp_f32_e32 v101, v101
	v_exp_f32_e32 v102, v102
	v_exp_f32_e32 v103, v103
	v_mfma_f32_32x32x16_bf16 v[112:127], v[232:235], v[146:149], v[80:95]
	ds_read_b128 v[232:235], v215 offset:53792
	s_waitcnt lgkmcnt(0)
	v_mfma_f32_32x32x16_bf16 v[112:127], v[232:235], v[150:153], v[112:127]
	ds_read_b128 v[236:239], v215 offset:49216
	ds_read_b128 v[232:235], v215 offset:53824
	s_waitcnt lgkmcnt(1)
	v_mfma_f32_32x32x16_bf16 v[128:143], v[236:239], v[154:157], v[128:143]
	s_waitcnt lgkmcnt(0)
	v_mfma_f32_32x32x16_bf16 v[112:127], v[232:235], v[154:157], v[112:127]
	ds_read_b128 v[232:235], v215 offset:53856
	ds_read_b128 v[236:239], v215 offset:49248
	v_exp_f32_e32 v215, v98
	v_exp_f32_e32 v98, v104
	v_exp_f32_e32 v104, v105
	v_exp_f32_e32 v105, v106
	v_exp_f32_e32 v106, v107
	v_exp_f32_e32 v107, v108
	v_exp_f32_e32 v108, v109
	v_exp_f32_e32 v109, v110
	v_exp_f32_e32 v110, v111
	v_add_f32_e32 v111, 0, v175
	v_add_f32_e32 v111, v176, v111
	v_add_f32_e32 v111, v177, v111
	v_add_f32_e32 v111, v178, v111
	v_add_f32_e32 v111, v179, v111
	v_add_f32_e32 v111, v181, v111
	v_add_f32_e32 v111, v183, v111
	v_add_f32_e32 v111, v185, v111
	v_add_f32_e32 v111, v180, v111
	v_add_f32_e32 v111, v182, v111
	v_add_f32_e32 v111, v184, v111
	v_add_f32_e32 v111, v227, v111
	v_add_f32_e32 v111, v228, v111
	v_add_f32_e32 v111, v229, v111
	v_add_f32_e32 v111, v230, v111
	v_add_f32_e32 v111, v174, v111
	v_add_f32_e32 v111, v96, v111
	v_add_f32_e32 v111, v97, v111
	v_add_f32_e32 v111, v215, v111
	v_add_f32_e32 v111, v99, v111
	v_add_f32_e32 v111, v100, v111
	v_add_f32_e32 v111, v101, v111
	v_add_f32_e32 v111, v102, v111
	s_waitcnt lgkmcnt(0)
	v_mfma_f32_32x32x16_bf16 v[128:143], v[236:239], v[158:161], v[128:143]
	v_add_f32_e32 v111, v103, v111
	v_add_f32_e32 v111, v98, v111
	v_add_f32_e32 v111, v104, v111
	v_add_f32_e32 v111, v105, v111
	v_add_f32_e32 v111, v106, v111
	v_add_f32_e32 v111, v107, v111
	v_add_f32_e32 v111, v108, v111
	v_add_f32_e32 v111, v109, v111
	v_add_f32_e32 v224, v110, v111
	s_nop 2
	v_max_f32_e32 v111, v129, v129
	v_max_f32_e32 v226, v128, v128
	v_mfma_f32_32x32x16_bf16 v[112:127], v[232:235], v[158:161], v[112:127]
	v_max_f32_e32 v111, v226, v111
	v_max3_f32 v111, v111, v130, v131
	v_max3_f32 v111, v111, v132, v133
	v_max3_f32 v111, v111, v134, v135
	v_max3_f32 v111, v111, v136, v137
	v_max3_f32 v111, v111, v138, v139
	v_max3_f32 v111, v111, v140, v141
	v_max3_f32 v111, v111, v142, v143
	s_nop 3
	v_max3_f32 v111, v111, v112, v113
	v_max3_f32 v111, v111, v114, v115
	v_max3_f32 v111, v111, v116, v117
	v_max3_f32 v111, v111, v118, v119
	v_max3_f32 v111, v111, v120, v121
	v_max3_f32 v111, v111, v122, v123
	v_max3_f32 v111, v111, v124, v125
	v_max3_f32 v111, v111, v126, v127
	v_mov_b32_e32 v226, v111
	s_nop 1
	v_permlane32_swap_b32_e32 v111, v226
	v_max_f32_e32 v226, v226, v226
	v_max_f32_e32 v111, v111, v111
	v_max_f32_e32 v111, v111, v226
	v_mov_b32_e32 v225, v224
	v_cmp_ge_f32_e32 vcc, s42, v111
	s_nop 0
	v_permlane32_swap_b32_e32 v224, v225
	s_cmp_eq_u64 vcc, exec
	s_cbranch_scc0 .LBB0_1301
	v_mov_b32_e32 v226, 1.0

; __device__ __forceinline__ void finishSM(f32x16& p0, f32x16& p1, float alpha, float& l_reg, bf16x8& pa0, bf16x8& pa1, bf16x8& pa2, bf16x8& pa3) {
; #pragma unroll
;   for (int r = 0; r < 16; ++r) p1[r] = __builtin_amdgcn_exp2f(p1[r]);
;   float ps = 0;
; #pragma unroll
;   for (int r = 0; r < 16; ++r) ps += p0[r];
; #pragma unroll
;   for (int r = 0; r < 16; ++r) ps += p1[r];
;   { auto rr = __builtin_amdgcn_permlane32_swap(__float_as_uint(ps), __float_as_uint(ps), false, false);
;     ps = __uint_as_float(rr[0]) + __uint_as_float(rr[1]); }
;   l_reg = l_reg * alpha + ps;
; template <int NQK>
; __device__ __forceinline__ void qkt_mi(f32x16& p0, f32x16& p1, const char* Ks, const bf16x8* qr, int r32, int hi, const f32x16& minit) {
;   constexpr int KROW = NQK * 32 + 16;
; #pragma unroll
;   for (int d0 = 0; d0 < NQK; ++d0) { const int cb = (d0 * 16 + hi * 8) * 2;
;     bf16x8 b0 = *reinterpret_cast<const bf16x8*>(Ks + r32 * KROW + cb);
;     bf16x8 b1 = *reinterpret_cast<const bf16x8*>(Ks + (32 + r32) * KROW + cb);
;     if (d0 == 0) { p0 = __builtin_amdgcn_mfma_f32_32x32x16_bf16(b0, qr[0], minit, 0, 0, 0); p1 = __builtin_amdgcn_mfma_f32_32x32x16_bf16(b1, qr[0], minit, 0, 0, 0); }
;     else { p0 = __builtin_amdgcn_mfma_f32_32x32x16_bf16(b0, qr[d0], p0, 0, 0, 0); p1 = __builtin_amdgcn_mfma_f32_32x32x16_bf16(b1, qr[d0], p1, 0, 0, 0); } }
; }
; __device__ __forceinline__ void decide_mi(f32x16& p0, f32x16& p1, f32x16& minit, float& M, float& alpha, const float thr2, const bool first) {
;   float pmax = p0[0];
; #pragma unroll
;   for (int r = 1; r < 16; ++r) pmax = fmaxf(pmax, p0[r]);
; #pragma unroll
;   for (int r = 0; r < 16; ++r) pmax = fmaxf(pmax, p1[r]);
;   { auto rr = __builtin_amdgcn_permlane32_swap(__float_as_uint(pmax), __float_as_uint(pmax), false, false);
;     pmax = fmaxf(__uint_as_float(rr[0]), __uint_as_float(rr[1])); }
;   if (__builtin_expect(!first && __all(pmax <= thr2), 1)) { alpha = 1.f; }
;   else { const float delta = first ? pmax : fmaxf(pmax, 0.f); alpha = first ? 1.f : __builtin_amdgcn_exp2f(-delta); M += delta;
; #pragma unroll
;     for (int r = 0; r < 16; ++r) { p0[r] -= delta; p1[r] -= delta; minit[r] = -M; } }
; }
.LBB0_1292:
	v_exp_f32_e32 v227, v128
	v_exp_f32_e32 v229, v129
	v_exp_f32_e32 v230, v130
	v_exp_f32_e32 v233, v131
	v_exp_f32_e32 v234, v132
	v_exp_f32_e32 v237, v133
	v_exp_f32_e32 v238, v134
	v_exp_f32_e32 v241, v135
	v_exp_f32_e32 v228, v136
	v_exp_f32_e32 v231, v137
	v_exp_f32_e32 v232, v138
	v_exp_f32_e32 v235, v139
	v_exp_f32_e32 v236, v140
	v_exp_f32_e32 v239, v141
	v_exp_f32_e32 v240, v142
	v_exp_f32_e32 v242, v143
	s_waitcnt lgkmcnt(0)
	s_barrier
	v_add_u32_e32 v243, s11, v221
	ds_read_b128 v[244:247], v243 offset:53760
	ds_read_b128 v[96:99], v243 offset:49152
	ds_read_b128 v[248:251], v243 offset:49184
	v_exp_f32_e32 v115, v115
	v_exp_f32_e32 v119, v119
	s_waitcnt lgkmcnt(1)
	v_mfma_f32_32x32x16_bf16 v[128:143], v[96:99], v[146:149], v[64:79]
	v_mfma_f32_32x32x16_bf16 v[96:111], v[244:247], v[146:149], v[64:79]
	ds_read_b128 v[244:247], v243 offset:53792
	s_waitcnt lgkmcnt(1)
	v_mfma_f32_32x32x16_bf16 v[128:143], v[248:251], v[150:153], v[128:143]
	s_waitcnt lgkmcnt(0)
	v_mfma_f32_32x32x16_bf16 v[96:111], v[244:247], v[150:153], v[96:111]
	ds_read_b128 v[248:251], v243 offset:49216
	ds_read_b128 v[244:247], v243 offset:53824
	s_waitcnt lgkmcnt(1)
	v_mfma_f32_32x32x16_bf16 v[128:143], v[248:251], v[154:157], v[128:143]
	s_waitcnt lgkmcnt(0)
	v_mfma_f32_32x32x16_bf16 v[96:111], v[244:247], v[154:157], v[96:111]
	ds_read_b128 v[244:247], v243 offset:53856
	ds_read_b128 v[248:251], v243 offset:49248
	v_exp_f32_e32 v243, v112
	v_add_f32_e32 v112, 0, v227
	v_add_f32_e32 v112, v229, v112
	v_add_f32_e32 v112, v230, v112
	v_add_f32_e32 v112, v233, v112
	v_add_f32_e32 v112, v234, v112
	v_add_f32_e32 v112, v237, v112
	v_add_f32_e32 v112, v238, v112
	v_add_f32_e32 v112, v241, v112
	v_add_f32_e32 v112, v228, v112
	v_add_f32_e32 v112, v231, v112
	v_add_f32_e32 v112, v232, v112
	v_add_f32_e32 v112, v235, v112
	v_add_f32_e32 v112, v236, v112
	s_waitcnt lgkmcnt(1)
	v_mfma_f32_32x32x16_bf16 v[96:111], v[244:247], v[158:161], v[96:111]
	v_exp_f32_e32 v244, v113
	v_add_f32_e32 v112, v239, v112
	v_exp_f32_e32 v245, v114
	v_add_f32_e32 v112, v240, v112
	v_add_f32_e32 v112, v242, v112
	v_exp_f32_e32 v246, v116
	v_add_f32_e32 v112, v243, v112
	v_exp_f32_e32 v247, v117
	v_add_f32_e32 v112, v244, v112
	s_waitcnt lgkmcnt(0)
	v_mfma_f32_32x32x16_bf16 v[128:143], v[248:251], v[158:161], v[128:143]
	v_exp_f32_e32 v248, v118
	v_add_f32_e32 v112, v245, v112
	v_add_f32_e32 v112, v115, v112
	v_exp_f32_e32 v116, v120
	v_add_f32_e32 v112, v246, v112
	v_exp_f32_e32 v117, v121
	v_add_f32_e32 v112, v247, v112
	v_exp_f32_e32 v118, v122
	v_add_f32_e32 v112, v248, v112
	v_exp_f32_e32 v120, v123
	v_add_f32_e32 v112, v119, v112
	v_exp_f32_e32 v121, v124
	v_add_f32_e32 v112, v116, v112
	v_exp_f32_e32 v122, v125
	v_add_f32_e32 v112, v117, v112
	v_exp_f32_e32 v123, v126
	v_add_f32_e32 v112, v118, v112
	v_exp_f32_e32 v124, v127
	v_add_f32_e32 v112, v120, v112
	v_add_f32_e32 v112, v121, v112
	v_add_f32_e32 v112, v122, v112
	v_add_f32_e32 v112, v123, v112
	v_add_f32_e32 v113, v124, v112
	v_max_f32_e32 v112, v129, v129
	v_max_f32_e32 v125, v128, v128
	v_max_f32_e32 v112, v125, v112
	v_max3_f32 v112, v112, v130, v131
	v_max3_f32 v112, v112, v132, v133
	v_max3_f32 v112, v112, v134, v135
	v_max3_f32 v112, v112, v136, v137
	v_max3_f32 v112, v112, v138, v139
	v_max3_f32 v112, v112, v140, v141
	v_max3_f32 v112, v112, v142, v143
	v_max3_f32 v112, v112, v96, v97
	v_max3_f32 v112, v112, v98, v99
	v_max3_f32 v112, v112, v100, v101
	v_max3_f32 v112, v112, v102, v103
	v_max3_f32 v112, v112, v104, v105
	v_max3_f32 v112, v112, v106, v107
	v_max3_f32 v112, v112, v108, v109
	v_max3_f32 v112, v112, v110, v111
	v_mov_b32_e32 v125, v112
	s_nop 1
	v_permlane32_swap_b32_e32 v112, v125
	v_max_f32_e32 v125, v125, v125
	v_max_f32_e32 v112, v112, v112
	v_max_f32_e32 v125, v112, v125
	v_mov_b32_e32 v114, v113
	v_cmp_ge_f32_e32 vcc, s42, v125
	s_nop 0
	v_permlane32_swap_b32_e32 v113, v114
	v_mov_b32_e32 v112, 1.0
	s_cmp_eq_u64 vcc, exec
	s_cbranch_scc0 .LBB0_1302
